# SwiGLU epilogue row-statistic loads issued in the last K iteration; epilogue waits with counted vmcnt(16) instead of draining the next tile prefetch
# speedup vs baseline: 1.0269x; 1.0048x over previous
; template <class Epi, class Sched, bool ALIGN_EPI = false, bool SP2 = false>
; __device__ __forceinline__ void gemm_phase(PG8_LAS unsigned char* lds, const Gemm g, const Sched& S, const Epi& E, int tid_in) {
;     ...
;         const bool has_next = S.next(ui + 1, nxt);
;         const char* nA = has_next ? (const char*)g.A + (size_t)nxt.pm * tstep : cA; const char* nB = has_next ? (const char*)g.Bt + (size_t)nxt.pn * tstep : cB;
;         constexpr int NHK = Epi::HAS_MID ? 2 : 1;
; #pragma unroll
;         for (int hk = 0; hk < NHK; ++hk) {
;         if constexpr (Epi::HAS_MID) { if (hk == 1) E.mid(acc, cur, wr, fr); }
;         const int t_beg = hk * (nt / NHK), t_end = (hk + 1) * (nt / NHK);
;         for (int t = t_beg; t < t_end; t += 2) {
;             const bool last = (t == nt - 2);
;             const char* a1 = cA + (size_t)(t + 1) * kstep;
;             const char* a2 = last ? nA : cA + (size_t)(t + 2) * kstep; const char* b2 = last ? nB : cB + (size_t)(t + 2) * kstep;
;             const char* a3 = a2 + kstep; const char* b3 = b2 + kstep;
;             if (last && has_next) S.a_ready(nxt);
;             if constexpr (SP2) {
;             PG8_LDB(B0, 0, 0); PG8_LDB(B1, 0, 1); PG8_SCHED; PG8_LDA(At, 0, 0); PG8_STAGE(PG8_SA(1, 1), a1 + hstep, voffA);
;             PG8_WAIT_V(8); PG8_WAIT_L(0); PG8_BAR; PG8_MMA(0, 0, At, B0); PG8_MMA(0, 1, At, B1); PG8_BAR; PG8_SCHED;
;             PG8_LDA(At, 0, 1); PG8_STAGE(PG8_SB(0, 0), b2, voffB); PG8_STAGE(PG8_SB(0, 1), b2 + hstep, voffB); PG8_STAGE(PG8_SA(0, 0), a2, voffA);
;             PG8_WAIT_V(8); PG8_WAIT_L(0); PG8_BAR; PG8_MMA(1, 0, At, B0); PG8_MMA(1, 1, At, B1); PG8_BAR; PG8_SCHED;
;             PG8_LDB(B0, 1, 0); PG8_LDB(B1, 1, 1); PG8_SCHED; PG8_LDA(At, 1, 0); PG8_STAGE(PG8_SA(0, 1), a2 + hstep, voffA);
;             PG8_WAIT_V(8); PG8_WAIT_L(0); PG8_BAR; PG8_MMA(0, 0, At, B0); PG8_MMA(0, 1, At, B1); PG8_BAR; PG8_SCHED;
;             PG8_LDA(At, 1, 1); PG8_STAGE(PG8_SB(1, 0), b3, voffB); PG8_STAGE(PG8_SB(1, 1), b3 + hstep, voffB); PG8_STAGE(PG8_SA(1, 0), a3, voffA);
;             PG8_WAIT_V(8); PG8_WAIT_L(0); PG8_BAR; PG8_MMA(1, 0, At, B0); PG8_MMA(1, 1, At, B1); PG8_BAR; PG8_SCHED;
;             } else {
;             PG8_LDB(B0, 0, 0); PG8_SCHED; PG8_LDA(At, 0, 0); PG8_STAGE(PG8_SA(1, 1), a1 + hstep, voffA);
;             PG8_WAIT_L(8); PG8_BAR; PG8_WAIT_L(0); PG8_MMA(0, 0, At, B0); PG8_BAR; PG8_SCHED;
.LBB0_25:
	s_ashr_i32 s35, s34, 31
	s_lshl_b64 s[10:11], s[34:35], 20
	s_add_u32 s36, s20, s10
	s_addc_u32 s37, s21, s11
	s_and_b64 s[10:11], s[38:39], exec
	s_cselect_b32 s10, s37, s45
	s_cselect_b32 s11, s36, s44
	s_ashr_i32 s31, s30, 31
	s_lshl_b64 s[14:15], s[30:31], 20
	s_add_u32 s40, s8, s14
	s_addc_u32 s41, s9, s15
	s_and_b64 s[14:15], s[38:39], exec
	s_cselect_b32 s31, s41, s43
	s_cselect_b32 s35, s40, s42
	s_add_u32 s83, s42, 0x100
	s_addc_u32 s84, s43, 0
	s_add_u32 s42, s44, 0x80080
	v_mov_b32_e32 v0, 0
	s_addc_u32 s43, s45, 0
	s_mov_b32 s85, -2
	v_mov_b32_e32 v1, v0
	v_mov_b32_e32 v2, v0
	v_mov_b32_e32 v3, v0
	v_mov_b32_e32 v8, v0
	v_mov_b32_e32 v9, v0
	v_mov_b32_e32 v10, v0
	v_mov_b32_e32 v11, v0
	v_mov_b32_e32 v20, v0
	v_mov_b32_e32 v21, v0
	v_mov_b32_e32 v22, v0
	v_mov_b32_e32 v23, v0
	v_mov_b32_e32 v24, v0
	v_mov_b32_e32 v25, v0
	v_mov_b32_e32 v26, v0
	v_mov_b32_e32 v27, v0
	v_mov_b32_e32 v36, v0
	v_mov_b32_e32 v37, v0
	v_mov_b32_e32 v38, v0
	v_mov_b32_e32 v39, v0
	v_mov_b32_e32 v40, v0
	v_mov_b32_e32 v41, v0
	v_mov_b32_e32 v42, v0
	v_mov_b32_e32 v43, v0
	v_mov_b32_e32 v52, v0
	v_mov_b32_e32 v53, v0
	v_mov_b32_e32 v54, v0
	v_mov_b32_e32 v55, v0
	v_mov_b32_e32 v56, v0
	v_mov_b32_e32 v57, v0
	v_mov_b32_e32 v58, v0
	v_mov_b32_e32 v59, v0
	v_mov_b32_e32 v4, v0
	v_mov_b32_e32 v5, v0
	v_mov_b32_e32 v6, v0
	v_mov_b32_e32 v7, v0
	v_mov_b32_e32 v12, v0
	v_mov_b32_e32 v13, v0
	v_mov_b32_e32 v14, v0
	v_mov_b32_e32 v15, v0
	v_mov_b32_e32 v16, v0
	v_mov_b32_e32 v17, v0
	v_mov_b32_e32 v18, v0
	v_mov_b32_e32 v19, v0
	v_mov_b32_e32 v28, v0
	v_mov_b32_e32 v29, v0
	v_mov_b32_e32 v30, v0
	v_mov_b32_e32 v31, v0
	v_mov_b32_e32 v32, v0
	v_mov_b32_e32 v33, v0
	v_mov_b32_e32 v34, v0
	v_mov_b32_e32 v35, v0
	v_mov_b32_e32 v44, v0
	v_mov_b32_e32 v45, v0
	v_mov_b32_e32 v46, v0
	v_mov_b32_e32 v47, v0
	v_mov_b32_e32 v48, v0
	v_mov_b32_e32 v49, v0
	v_mov_b32_e32 v50, v0
	v_mov_b32_e32 v51, v0
	v_mov_b32_e32 v60, v0
	v_mov_b32_e32 v61, v0
	v_mov_b32_e32 v62, v0
	v_mov_b32_e32 v63, v0
	v_mov_b32_e32 v68, v0
	v_mov_b32_e32 v69, v0
	v_mov_b32_e32 v70, v0
	v_mov_b32_e32 v71, v0
	v_mov_b32_e32 v72, v0
	v_mov_b32_e32 v73, v0
	v_mov_b32_e32 v74, v0
	v_mov_b32_e32 v75, v0
	v_mov_b32_e32 v84, v0
	v_mov_b32_e32 v85, v0
	v_mov_b32_e32 v86, v0
	v_mov_b32_e32 v87, v0
	v_mov_b32_e32 v88, v0
	v_mov_b32_e32 v89, v0
	v_mov_b32_e32 v90, v0
	v_mov_b32_e32 v91, v0
	v_mov_b32_e32 v100, v0
	v_mov_b32_e32 v101, v0
	v_mov_b32_e32 v102, v0
	v_mov_b32_e32 v103, v0
	v_mov_b32_e32 v104, v0
	v_mov_b32_e32 v105, v0
	v_mov_b32_e32 v106, v0
	v_mov_b32_e32 v107, v0
	v_mov_b32_e32 v116, v0
	v_mov_b32_e32 v117, v0
	v_mov_b32_e32 v118, v0
	v_mov_b32_e32 v119, v0
	v_mov_b32_e32 v120, v0
	v_mov_b32_e32 v121, v0
	v_mov_b32_e32 v122, v0
	v_mov_b32_e32 v123, v0
	v_mov_b32_e32 v64, v0
	v_mov_b32_e32 v65, v0
	v_mov_b32_e32 v66, v0
	v_mov_b32_e32 v67, v0
	v_mov_b32_e32 v76, v0
	v_mov_b32_e32 v77, v0
	v_mov_b32_e32 v78, v0
	v_mov_b32_e32 v79, v0
	v_mov_b32_e32 v80, v0
	v_mov_b32_e32 v81, v0
	v_mov_b32_e32 v82, v0
	v_mov_b32_e32 v83, v0
	v_mov_b32_e32 v92, v0
	v_mov_b32_e32 v93, v0
	v_mov_b32_e32 v94, v0
	v_mov_b32_e32 v95, v0
	v_mov_b32_e32 v96, v0
	v_mov_b32_e32 v97, v0
	v_mov_b32_e32 v98, v0
	v_mov_b32_e32 v99, v0
	v_mov_b32_e32 v108, v0
	v_mov_b32_e32 v109, v0
	v_mov_b32_e32 v110, v0
	v_mov_b32_e32 v111, v0
	v_mov_b32_e32 v112, v0
	v_mov_b32_e32 v113, v0
	v_mov_b32_e32 v114, v0
	v_mov_b32_e32 v115, v0
	v_mov_b32_e32 v124, v0
	v_mov_b32_e32 v125, v0
	v_mov_b32_e32 v126, v0
	v_mov_b32_e32 v127, v0
	v_lshl_add_u32 v228, s2, 8, v140
	v_ashrrev_i32_e32 v229, 31, v228
	v_lshl_add_u64 v[228:229], v[228:229], 2, s[26:27]
.LBB0_26:
	s_add_u32 s14, s42, 0xfff80080
	s_addc_u32 s15, s43, -1
	s_add_u32 s100, s42, 0xfff80000
	s_addc_u32 s101, s43, -1
	s_add_i32 s86, 0, 0x10000
	s_cmp_eq_u32 s85, 28
	s_cselect_b32 s15, s10, s15
	s_cselect_b32 s14, s11, s14
	v_add_u32_e32 v138, s86, v141
	s_cselect_b32 s45, s31, s84
	s_cselect_b32 s44, s35, s83
	s_cbranch_scc0 .Lss_skip
	global_load_dword v194, v[228:229], off
	global_load_dword v195, v[228:229], off offset:64
	global_load_dword v196, v[228:229], off offset:128
	global_load_dword v197, v[228:229], off offset:192
	global_load_dword v198, v[228:229], off offset:512
	global_load_dword v199, v[228:229], off offset:576
	global_load_dword v200, v[228:229], off offset:640
	global_load_dword v201, v[228:229], off offset:704
; #define PG8_STAGE(bufoff, gbase, voff) do { _Pragma("unroll") for (int _i = 0; _i < 2; ++_i) \
;         __builtin_amdgcn_global_load_lds((const unsigned*)((const char*)(gbase) + (voff)[_i]), (PG8_LAS unsigned*)(lds + (bufoff) + ldsw + _i * 8192), 16, 0, 0); } while (0)
; #define PG8_LDA(dst, b, h) do { _Pragma("unroll") for (int m = 0; m < 4; ++m) _Pragma("unroll") for (int k = 0; k < 2; ++k) dst[m][k] = *(const PG8_LAS bf16x8*)(lds + PG8_SA(b, h) + aoff + m * 2048 + k * 1024); } while (0)
; #define PG8_LDB(dst, b, h) do { _Pragma("unroll") for (int n = 0; n < 2; ++n) _Pragma("unroll") for (int k = 0; k < 2; ++k) dst[n][k] = *(const PG8_LAS bf16x8*)(lds + PG8_SB(b, h) + boff + n * 2048 + k * 1024); } while (0)
; #define PG8_MMA(ai, bj, At, Bt) do { __builtin_amdgcn_s_setprio(1); _Pragma("unroll") for (int m = 0; m < 4; ++m) _Pragma("unroll") for (int n = 0; n < 2; ++n) _Pragma("unroll") for (int k = 0; k < 2; ++k) \
;         acc[ai][bj][m][n] = __builtin_amdgcn_mfma_f32_16x16x32_bf16(Bt[n][k], At[m][k], acc[ai][bj][m][n], 0, 0, 0); __builtin_amdgcn_s_setprio(0); } while (0)
; #define PG8_WAIT_V(n) asm volatile("s_waitcnt vmcnt(" #n ")" ::: "memory")
; #define PG8_WAIT_L(n) asm volatile("s_waitcnt lgkmcnt(" #n ")" ::: "memory")
; #define PG8_BAR __builtin_amdgcn_s_barrier()
; #define PG8_SCHED __builtin_amdgcn_sched_barrier(0)
; template <class Epi, class Sched, bool ALIGN_EPI = false, bool SP2 = false>
; __device__ __forceinline__ void gemm_phase(PG8_LAS unsigned char* lds, const Gemm g, const Sched& S, const Epi& E, int tid_in) {
;     ...
;             if constexpr (SP2) {
;             PG8_LDB(B0, 0, 0); PG8_LDB(B1, 0, 1); PG8_SCHED; PG8_LDA(At, 0, 0); PG8_STAGE(PG8_SA(1, 1), a1 + hstep, voffA);
;             PG8_WAIT_V(8); PG8_WAIT_L(0); PG8_BAR; PG8_MMA(0, 0, At, B0); PG8_MMA(0, 1, At, B1); PG8_BAR; PG8_SCHED;
;             PG8_LDA(At, 0, 1); PG8_STAGE(PG8_SB(0, 0), b2, voffB); PG8_STAGE(PG8_SB(0, 1), b2 + hstep, voffB); PG8_STAGE(PG8_SA(0, 0), a2, voffA);
;             PG8_WAIT_V(8); PG8_WAIT_L(0); PG8_BAR; PG8_MMA(1, 0, At, B0); PG8_MMA(1, 1, At, B1); PG8_BAR; PG8_SCHED;
.Lss_skip:
	s_add_i32 s88, 0, 0x14000
	s_add_u32 s98, s44, 0x80
	s_addc_u32 s99, s45, 0
	ds_read_b128 v[144:147], v138
	ds_read_b128 v[148:151], v138 offset:1024
	ds_read_b128 v[152:155], v138 offset:2048
	ds_read_b128 v[156:159], v138 offset:3072
	v_add_u32_e32 v138, s88, v141
	ds_read_b128 v[160:163], v138
	ds_read_b128 v[164:167], v138 offset:1024
	ds_read_b128 v[168:171], v138 offset:2048
	ds_read_b128 v[172:175], v138 offset:3072
	s_mov_b32 m0, s55
	ds_read_b128 v[176:179], v143
	ds_read_b128 v[180:183], v143 offset:1024
	ds_read_b128 v[184:187], v143 offset:2048
	ds_read_b128 v[188:191], v143 offset:3072
	ds_read_b128 v[212:215], v143 offset:4096
	ds_read_b128 v[216:219], v143 offset:5120
	ds_read_b128 v[220:223], v143 offset:6144
	ds_read_b128 v[224:227], v143 offset:7168
	global_load_lds_dwordx4 v132, s[100:101]
	s_mov_b32 m0, s56
	s_nop 0
	global_load_lds_dwordx4 v130, s[100:101]
	s_add_i32 m0, s51, 0xc000
	s_nop 0
	global_load_lds_dwordx4 v136, s[42:43]
	s_add_i32 m0, s51, 0xe000
	s_nop 0
	global_load_lds_dwordx4 v134, s[42:43]
	s_waitcnt vmcnt(8)
	s_waitcnt lgkmcnt(0)
	s_barrier
	s_setprio 1
	s_waitcnt lgkmcnt(0)
	v_mfma_f32_16x16x32_bf16 v[124:127], v[144:147], v[176:179], v[124:127]
	v_mfma_f32_16x16x32_bf16 v[112:115], v[152:155], v[176:179], v[112:115]
	v_mfma_f32_16x16x32_bf16 v[108:111], v[144:147], v[184:187], v[108:111]
	v_mfma_f32_16x16x32_bf16 v[96:99], v[152:155], v[184:187], v[96:99]
	v_mfma_f32_16x16x32_bf16 v[92:95], v[144:147], v[212:215], v[92:95]
	v_mfma_f32_16x16x32_bf16 v[80:83], v[152:155], v[212:215], v[80:83]
	v_mfma_f32_16x16x32_bf16 v[76:79], v[144:147], v[220:223], v[76:79]
	v_mfma_f32_16x16x32_bf16 v[64:67], v[152:155], v[220:223], v[64:67]
	v_mfma_f32_16x16x32_bf16 v[124:127], v[148:151], v[180:183], v[124:127]
	v_mfma_f32_16x16x32_bf16 v[112:115], v[156:159], v[180:183], v[112:115]
	v_mfma_f32_16x16x32_bf16 v[108:111], v[148:151], v[188:191], v[108:111]
	v_mfma_f32_16x16x32_bf16 v[96:99], v[156:159], v[188:191], v[96:99]
	v_mfma_f32_16x16x32_bf16 v[92:95], v[148:151], v[216:219], v[92:95]
	v_mfma_f32_16x16x32_bf16 v[80:83], v[156:159], v[216:219], v[80:83]
	v_mfma_f32_16x16x32_bf16 v[76:79], v[148:151], v[224:227], v[76:79]
	v_mfma_f32_16x16x32_bf16 v[64:67], v[156:159], v[224:227], v[64:67]
	s_setprio 0
	s_setprio 1
	v_mfma_f32_16x16x32_bf16 v[120:123], v[160:163], v[176:179], v[120:123]
	v_mfma_f32_16x16x32_bf16 v[116:119], v[168:171], v[176:179], v[116:119]
	v_mfma_f32_16x16x32_bf16 v[104:107], v[160:163], v[184:187], v[104:107]
	v_mfma_f32_16x16x32_bf16 v[100:103], v[168:171], v[184:187], v[100:103]
	v_mfma_f32_16x16x32_bf16 v[88:91], v[160:163], v[212:215], v[88:91]
	v_mfma_f32_16x16x32_bf16 v[84:87], v[168:171], v[212:215], v[84:87]
	v_mfma_f32_16x16x32_bf16 v[72:75], v[160:163], v[220:223], v[72:75]
	v_mfma_f32_16x16x32_bf16 v[68:71], v[168:171], v[220:223], v[68:71]
	v_mfma_f32_16x16x32_bf16 v[120:123], v[164:167], v[180:183], v[120:123]
	v_mfma_f32_16x16x32_bf16 v[116:119], v[172:175], v[180:183], v[116:119]
	v_mfma_f32_16x16x32_bf16 v[104:107], v[164:167], v[188:191], v[104:107]
	v_mfma_f32_16x16x32_bf16 v[100:103], v[172:175], v[188:191], v[100:103]
	v_mfma_f32_16x16x32_bf16 v[88:91], v[164:167], v[216:219], v[88:91]
	v_mfma_f32_16x16x32_bf16 v[84:87], v[172:175], v[216:219], v[84:87]
	v_mfma_f32_16x16x32_bf16 v[72:75], v[164:167], v[224:227], v[72:75]
	v_mfma_f32_16x16x32_bf16 v[68:71], v[172:175], v[224:227], v[68:71]
	s_setprio 0
	s_barrier
	s_add_i32 s86, s86, s46
	s_mov_b32 m0, s86
	ds_read_b128 v[176:179], v143 offset:16384
	ds_read_b128 v[180:183], v143 offset:17408
	ds_read_b128 v[184:187], v143 offset:18432
	ds_read_b128 v[188:191], v143 offset:19456
	ds_read_b128 v[212:215], v143 offset:20480
	ds_read_b128 v[216:219], v143 offset:21504
	ds_read_b128 v[220:223], v143 offset:22528
	ds_read_b128 v[224:227], v143 offset:23552
	global_load_lds_dwordx4 v192, s[44:45]
	s_add_i32 m0, s86, 0x2000
	s_add_u32 s86, s44, 0x80000
	s_addc_u32 s87, s45, 0
	s_add_i32 s88, s88, s46
	global_load_lds_dwordx4 v128, s[44:45]
	s_mov_b32 m0, s88
	s_nop 0
	global_load_lds_dwordx4 v192, s[86:87]
	s_add_i32 m0, s88, 0x2000
	s_nop 0
	global_load_lds_dwordx4 v128, s[86:87]
	s_waitcnt vmcnt(6)
	s_waitcnt lgkmcnt(0)
	s_barrier
	s_setprio 1
	s_waitcnt lgkmcnt(0)
	v_mfma_f32_16x16x32_bf16 v[60:63], v[144:147], v[176:179], v[60:63]
	v_mfma_f32_16x16x32_bf16 v[48:51], v[152:155], v[176:179], v[48:51]
	v_mfma_f32_16x16x32_bf16 v[44:47], v[144:147], v[184:187], v[44:47]
	v_mfma_f32_16x16x32_bf16 v[32:35], v[152:155], v[184:187], v[32:35]
	v_mfma_f32_16x16x32_bf16 v[28:31], v[144:147], v[212:215], v[28:31]
	v_mfma_f32_16x16x32_bf16 v[16:19], v[152:155], v[212:215], v[16:19]
	v_mfma_f32_16x16x32_bf16 v[12:15], v[144:147], v[220:223], v[12:15]
	v_mfma_f32_16x16x32_bf16 v[4:7], v[152:155], v[220:223], v[4:7]
	v_mfma_f32_16x16x32_bf16 v[60:63], v[148:151], v[180:183], v[60:63]
	v_mfma_f32_16x16x32_bf16 v[48:51], v[156:159], v[180:183], v[48:51]
	v_mfma_f32_16x16x32_bf16 v[44:47], v[148:151], v[188:191], v[44:47]
	v_mfma_f32_16x16x32_bf16 v[32:35], v[156:159], v[188:191], v[32:35]
	v_mfma_f32_16x16x32_bf16 v[28:31], v[148:151], v[216:219], v[28:31]
	v_mfma_f32_16x16x32_bf16 v[16:19], v[156:159], v[216:219], v[16:19]
	v_mfma_f32_16x16x32_bf16 v[12:15], v[148:151], v[224:227], v[12:15]
	v_mfma_f32_16x16x32_bf16 v[4:7], v[156:159], v[224:227], v[4:7]
	s_setprio 0
	s_setprio 1
	v_mfma_f32_16x16x32_bf16 v[56:59], v[160:163], v[176:179], v[56:59]
	v_mfma_f32_16x16x32_bf16 v[52:55], v[168:171], v[176:179], v[52:55]
	v_mfma_f32_16x16x32_bf16 v[40:43], v[160:163], v[184:187], v[40:43]
	v_mfma_f32_16x16x32_bf16 v[36:39], v[168:171], v[184:187], v[36:39]
	v_mfma_f32_16x16x32_bf16 v[24:27], v[160:163], v[212:215], v[24:27]
	v_mfma_f32_16x16x32_bf16 v[20:23], v[168:171], v[212:215], v[20:23]
	v_mfma_f32_16x16x32_bf16 v[8:11], v[160:163], v[220:223], v[8:11]
	v_mfma_f32_16x16x32_bf16 v[0:3], v[168:171], v[220:223], v[0:3]
	v_mfma_f32_16x16x32_bf16 v[56:59], v[164:167], v[180:183], v[56:59]
	v_mfma_f32_16x16x32_bf16 v[52:55], v[172:175], v[180:183], v[52:55]
	v_mfma_f32_16x16x32_bf16 v[40:43], v[164:167], v[188:191], v[40:43]
	v_mfma_f32_16x16x32_bf16 v[36:39], v[172:175], v[188:191], v[36:39]
	v_mfma_f32_16x16x32_bf16 v[24:27], v[164:167], v[216:219], v[24:27]
	v_mfma_f32_16x16x32_bf16 v[20:23], v[172:175], v[216:219], v[20:23]
	v_mfma_f32_16x16x32_bf16 v[8:11], v[164:167], v[224:227], v[8:11]
	v_mfma_f32_16x16x32_bf16 v[0:3], v[172:175], v[224:227], v[0:3]
	s_setprio 0
	s_barrier
; #define PG8_STAGE(bufoff, gbase, voff) do { _Pragma("unroll") for (int _i = 0; _i < 2; ++_i) \
;         __builtin_amdgcn_global_load_lds((const unsigned*)((const char*)(gbase) + (voff)[_i]), (PG8_LAS unsigned*)(lds + (bufoff) + ldsw + _i * 8192), 16, 0, 0); } while (0)
; #define PG8_LDA(dst, b, h) do { _Pragma("unroll") for (int m = 0; m < 4; ++m) _Pragma("unroll") for (int k = 0; k < 2; ++k) dst[m][k] = *(const PG8_LAS bf16x8*)(lds + PG8_SA(b, h) + aoff + m * 2048 + k * 1024); } while (0)
; #define PG8_LDB(dst, b, h) do { _Pragma("unroll") for (int n = 0; n < 2; ++n) _Pragma("unroll") for (int k = 0; k < 2; ++k) dst[n][k] = *(const PG8_LAS bf16x8*)(lds + PG8_SB(b, h) + boff + n * 2048 + k * 1024); } while (0)
; #define PG8_MMA(ai, bj, At, Bt) do { __builtin_amdgcn_s_setprio(1); _Pragma("unroll") for (int m = 0; m < 4; ++m) _Pragma("unroll") for (int n = 0; n < 2; ++n) _Pragma("unroll") for (int k = 0; k < 2; ++k) \
;         acc[ai][bj][m][n] = __builtin_amdgcn_mfma_f32_16x16x32_bf16(Bt[n][k], At[m][k], acc[ai][bj][m][n], 0, 0, 0); __builtin_amdgcn_s_setprio(0); } while (0)
; #define PG8_WAIT_V(n) asm volatile("s_waitcnt vmcnt(" #n ")" ::: "memory")
; #define PG8_WAIT_L(n) asm volatile("s_waitcnt lgkmcnt(" #n ")" ::: "memory")
; #define PG8_BAR __builtin_amdgcn_s_barrier()
; #define PG8_SCHED __builtin_amdgcn_sched_barrier(0)
; template <class Epi, class Sched, bool ALIGN_EPI = false, bool SP2 = false>
; __device__ __forceinline__ void gemm_phase(PG8_LAS unsigned char* lds, const Gemm g, const Sched& S, const Epi& E, int tid_in) {
;     ...
;             PG8_LDB(B0, 1, 0); PG8_LDB(B1, 1, 1); PG8_SCHED; PG8_LDA(At, 1, 0); PG8_STAGE(PG8_SA(0, 1), a2 + hstep, voffA);
;             PG8_WAIT_V(8); PG8_WAIT_L(0); PG8_BAR; PG8_MMA(0, 0, At, B0); PG8_MMA(0, 1, At, B1); PG8_BAR; PG8_SCHED;
;             PG8_LDA(At, 1, 1); PG8_STAGE(PG8_SB(1, 0), b3, voffB); PG8_STAGE(PG8_SB(1, 1), b3 + hstep, voffB); PG8_STAGE(PG8_SA(1, 0), a3, voffA);
;             PG8_WAIT_V(8); PG8_WAIT_L(0); PG8_BAR; PG8_MMA(1, 0, At, B0); PG8_MMA(1, 1, At, B1); PG8_BAR; PG8_SCHED;
	s_add_i32 s86, 0, 0x18000
	s_add_i32 s87, 0, 0x1c000
	v_add_u32_e32 v156, s86, v141
	v_add_u32_e32 v172, s87, v141
	ds_read_b128 v[144:147], v156
	ds_read_b128 v[148:151], v156 offset:1024
	ds_read_b128 v[152:155], v156 offset:2048
	ds_read_b128 v[156:159], v156 offset:3072
	ds_read_b128 v[160:163], v172
	ds_read_b128 v[164:167], v172 offset:1024
	ds_read_b128 v[168:171], v172 offset:2048
	ds_read_b128 v[172:175], v172 offset:3072
	s_mov_b64 s[100:101], s[14:15]
	s_add_u32 s14, s14, 0x80000
	s_addc_u32 s15, s15, 0
	s_mov_b32 m0, s51
	ds_read_b128 v[176:179], v143 offset:32768
	ds_read_b128 v[180:183], v143 offset:33792
	ds_read_b128 v[184:187], v143 offset:34816
	ds_read_b128 v[188:191], v143 offset:35840
	ds_read_b128 v[212:215], v143 offset:36864
	ds_read_b128 v[216:219], v143 offset:37888
	ds_read_b128 v[220:223], v143 offset:38912
	ds_read_b128 v[224:227], v143 offset:39936
	global_load_lds_dwordx4 v132, s[100:101]
	s_mov_b32 m0, s52
	s_nop 0
	global_load_lds_dwordx4 v130, s[100:101]
	s_mov_b32 m0, s53
	s_nop 0
	global_load_lds_dwordx4 v132, s[14:15]
	s_mov_b32 m0, s54
	s_nop 0
	global_load_lds_dwordx4 v130, s[14:15]
	s_waitcnt vmcnt(8)
	s_waitcnt lgkmcnt(0)
	s_barrier
	s_setprio 1
	s_waitcnt lgkmcnt(0)
	v_mfma_f32_16x16x32_bf16 v[124:127], v[144:147], v[176:179], v[124:127]
	v_mfma_f32_16x16x32_bf16 v[112:115], v[152:155], v[176:179], v[112:115]
	v_mfma_f32_16x16x32_bf16 v[108:111], v[144:147], v[184:187], v[108:111]
	v_mfma_f32_16x16x32_bf16 v[96:99], v[152:155], v[184:187], v[96:99]
	v_mfma_f32_16x16x32_bf16 v[92:95], v[144:147], v[212:215], v[92:95]
	v_mfma_f32_16x16x32_bf16 v[80:83], v[152:155], v[212:215], v[80:83]
	v_mfma_f32_16x16x32_bf16 v[76:79], v[144:147], v[220:223], v[76:79]
	v_mfma_f32_16x16x32_bf16 v[64:67], v[152:155], v[220:223], v[64:67]
	v_mfma_f32_16x16x32_bf16 v[124:127], v[148:151], v[180:183], v[124:127]
	v_mfma_f32_16x16x32_bf16 v[112:115], v[156:159], v[180:183], v[112:115]
	v_mfma_f32_16x16x32_bf16 v[108:111], v[148:151], v[188:191], v[108:111]
	v_mfma_f32_16x16x32_bf16 v[96:99], v[156:159], v[188:191], v[96:99]
	v_mfma_f32_16x16x32_bf16 v[92:95], v[148:151], v[216:219], v[92:95]
	v_mfma_f32_16x16x32_bf16 v[80:83], v[156:159], v[216:219], v[80:83]
	v_mfma_f32_16x16x32_bf16 v[76:79], v[148:151], v[224:227], v[76:79]
	v_mfma_f32_16x16x32_bf16 v[64:67], v[156:159], v[224:227], v[64:67]
	s_setprio 0
	s_setprio 1
	v_mfma_f32_16x16x32_bf16 v[120:123], v[160:163], v[176:179], v[120:123]
	v_mfma_f32_16x16x32_bf16 v[116:119], v[168:171], v[176:179], v[116:119]
	v_mfma_f32_16x16x32_bf16 v[104:107], v[160:163], v[184:187], v[104:107]
	v_mfma_f32_16x16x32_bf16 v[100:103], v[168:171], v[184:187], v[100:103]
	v_mfma_f32_16x16x32_bf16 v[88:91], v[160:163], v[212:215], v[88:91]
	v_mfma_f32_16x16x32_bf16 v[84:87], v[168:171], v[212:215], v[84:87]
	v_mfma_f32_16x16x32_bf16 v[72:75], v[160:163], v[220:223], v[72:75]
	v_mfma_f32_16x16x32_bf16 v[68:71], v[168:171], v[220:223], v[68:71]
	v_mfma_f32_16x16x32_bf16 v[120:123], v[164:167], v[180:183], v[120:123]
	v_mfma_f32_16x16x32_bf16 v[116:119], v[172:175], v[180:183], v[116:119]
	v_mfma_f32_16x16x32_bf16 v[104:107], v[164:167], v[188:191], v[104:107]
	v_mfma_f32_16x16x32_bf16 v[100:103], v[172:175], v[188:191], v[100:103]
	v_mfma_f32_16x16x32_bf16 v[88:91], v[164:167], v[216:219], v[88:91]
	v_mfma_f32_16x16x32_bf16 v[84:87], v[172:175], v[216:219], v[84:87]
	v_mfma_f32_16x16x32_bf16 v[72:75], v[164:167], v[224:227], v[72:75]
	v_mfma_f32_16x16x32_bf16 v[68:71], v[172:175], v[224:227], v[68:71]
	s_setprio 0
	s_barrier
	s_add_i32 s14, s86, s46
	s_mov_b32 m0, s14
	ds_read_b128 v[176:179], v143 offset:49152
	ds_read_b128 v[180:183], v143 offset:50176
	ds_read_b128 v[184:187], v143 offset:51200
	ds_read_b128 v[188:191], v143 offset:52224
	ds_read_b128 v[212:215], v143 offset:53248
	ds_read_b128 v[216:219], v143 offset:54272
	ds_read_b128 v[220:223], v143 offset:55296
	ds_read_b128 v[224:227], v143 offset:56320
	global_load_lds_dwordx4 v192, s[98:99]
	s_add_i32 m0, s14, 0x2000
	s_add_u32 s14, s44, 0x80080
	s_addc_u32 s15, s45, 0
	s_add_i32 s44, s87, s46
	global_load_lds_dwordx4 v128, s[98:99]
	s_mov_b32 m0, s44
	s_nop 0
	global_load_lds_dwordx4 v192, s[14:15]
	s_add_i32 m0, s44, 0x2000
	s_nop 0
	global_load_lds_dwordx4 v128, s[14:15]
	s_waitcnt vmcnt(6)
	s_waitcnt lgkmcnt(0)
	s_barrier
	s_setprio 1
	s_waitcnt lgkmcnt(0)
	v_mfma_f32_16x16x32_bf16 v[60:63], v[144:147], v[176:179], v[60:63]
	v_mfma_f32_16x16x32_bf16 v[48:51], v[152:155], v[176:179], v[48:51]
	v_mfma_f32_16x16x32_bf16 v[44:47], v[144:147], v[184:187], v[44:47]
	v_mfma_f32_16x16x32_bf16 v[32:35], v[152:155], v[184:187], v[32:35]
	v_mfma_f32_16x16x32_bf16 v[28:31], v[144:147], v[212:215], v[28:31]
	v_mfma_f32_16x16x32_bf16 v[16:19], v[152:155], v[212:215], v[16:19]
	v_mfma_f32_16x16x32_bf16 v[12:15], v[144:147], v[220:223], v[12:15]
	v_mfma_f32_16x16x32_bf16 v[4:7], v[152:155], v[220:223], v[4:7]
	v_mfma_f32_16x16x32_bf16 v[60:63], v[148:151], v[180:183], v[60:63]
	v_mfma_f32_16x16x32_bf16 v[48:51], v[156:159], v[180:183], v[48:51]
	v_mfma_f32_16x16x32_bf16 v[44:47], v[148:151], v[188:191], v[44:47]
	v_mfma_f32_16x16x32_bf16 v[32:35], v[156:159], v[188:191], v[32:35]
	v_mfma_f32_16x16x32_bf16 v[28:31], v[148:151], v[216:219], v[28:31]
	v_mfma_f32_16x16x32_bf16 v[16:19], v[156:159], v[216:219], v[16:19]
	v_mfma_f32_16x16x32_bf16 v[12:15], v[148:151], v[224:227], v[12:15]
	v_mfma_f32_16x16x32_bf16 v[4:7], v[156:159], v[224:227], v[4:7]
	s_setprio 0
	s_setprio 1
	v_mfma_f32_16x16x32_bf16 v[56:59], v[160:163], v[176:179], v[56:59]
	v_mfma_f32_16x16x32_bf16 v[52:55], v[168:171], v[176:179], v[52:55]
	v_mfma_f32_16x16x32_bf16 v[40:43], v[160:163], v[184:187], v[40:43]
	v_mfma_f32_16x16x32_bf16 v[36:39], v[168:171], v[184:187], v[36:39]
	v_mfma_f32_16x16x32_bf16 v[24:27], v[160:163], v[212:215], v[24:27]
	v_mfma_f32_16x16x32_bf16 v[20:23], v[168:171], v[212:215], v[20:23]
	v_mfma_f32_16x16x32_bf16 v[8:11], v[160:163], v[220:223], v[8:11]
	v_mfma_f32_16x16x32_bf16 v[0:3], v[168:171], v[220:223], v[0:3]
	v_mfma_f32_16x16x32_bf16 v[56:59], v[164:167], v[180:183], v[56:59]
	v_mfma_f32_16x16x32_bf16 v[52:55], v[172:175], v[180:183], v[52:55]
	v_mfma_f32_16x16x32_bf16 v[40:43], v[164:167], v[188:191], v[40:43]
	v_mfma_f32_16x16x32_bf16 v[36:39], v[172:175], v[188:191], v[36:39]
	v_mfma_f32_16x16x32_bf16 v[24:27], v[164:167], v[216:219], v[24:27]
	v_mfma_f32_16x16x32_bf16 v[20:23], v[172:175], v[216:219], v[20:23]
	v_mfma_f32_16x16x32_bf16 v[8:11], v[164:167], v[224:227], v[8:11]
	v_mfma_f32_16x16x32_bf16 v[0:3], v[172:175], v[224:227], v[0:3]
	s_setprio 0
	s_barrier
	s_add_i32 s85, s85, 2
	s_add_u32 s83, s83, 0x100
	s_addc_u32 s84, s84, 0
	s_add_u32 s42, s42, 0x100
	s_addc_u32 s43, s43, 0
	s_cmp_gt_u32 s85, 29
	s_cbranch_scc0 .LBB0_26
	s_and_b64 vcc, exec, s[28:29]
	s_cbranch_vccz .LBB0_29
	s_barrier
; __device__ __forceinline__ unsigned cvt_pk_bf16(float lo, float hi) { unsigned r; asm volatile("v_cvt_pk_bf16_f32 %0, %1, %2" : "=v"(r) : "v"(lo), "v"(hi)); return r; }
; __device__ __forceinline__ float rstd_of(float ss, float inv_n) { return __builtin_amdgcn_rsqf(ss * inv_n + RMS_EPS); }
;     __device__ __forceinline__ void operator()(const f32x4 (&acc)[2][2][4][2], const Unit& u, int wr, int wc, int fr, int fq) const {
;         const int row0 = u.pm * BM + wr * 64 + fr; const int col0 = u.pn * HALF + wc * 32 + 8 * fq;
;         float rsv[2][4];
; #pragma unroll
;         for (int ai = 0; ai < 2; ++ai)
; #pragma unroll
;             for (int m = 0; m < 4; ++m) rsv[ai][m] = gld<float>(ss + row0 + ai * HALF + m * 16);
;         __builtin_amdgcn_sched_barrier(0);
; #pragma unroll
;         for (int ai = 0; ai < 2; ++ai)
; #pragma unroll
;             for (int m = 0; m < 4; ++m) {
;                 const int row = row0 + ai * HALF + m * 16;
;                 const float rs = rstd_of(rsv[ai][m], 1.0f / 2048.0f);
;                 float v[8];
;                 const float cneg = rs * -1.44269504089f, rs2 = rs * rs;
; #pragma unroll
;                 for (int n = 0; n < 2; ++n)
; #pragma unroll
;                     for (int hh = 0; hh < 2; ++hh) {
;                         const f32x2 g = (f32x2){acc[ai][0][m][n][2 * hh], acc[ai][0][m][n][2 * hh + 1]}, up = (f32x2){acc[ai][1][m][n][2 * hh], acc[ai][1][m][n][2 * hh + 1]};
;                         const f32x2 t = g * cneg;
;                         f32x2 d; d.x = __builtin_amdgcn_exp2f(t.x); d.y = __builtin_amdgcn_exp2f(t.y); d = d + 1.0f;
;                         f32x2 r; r.x = __builtin_amdgcn_rcpf(d.x); r.y = __builtin_amdgcn_rcpf(d.y);
;                         const f32x2 o = (g * up) * (r * rs2);
;                         v[n * 4 + 2 * hh] = o.x; v[n * 4 + 2 * hh + 1] = o.y;
;                     }
;                 u32x4 w; w.x = cvt_pk_bf16(v[0], v[1]); w.y = cvt_pk_bf16(v[2], v[3]); w.z = cvt_pk_bf16(v[4], v[5]); w.w = cvt_pk_bf16(v[6], v[7]);
;                 gst<u32x4>(O + (size_t)row * ldo + col0, w);
;             }
.LBB0_29:
	v_lshl_add_u32 v138, s2, 8, v140
	v_lshl_or_b32 v148, s3, 7, v142
	s_waitcnt vmcnt(16)
	v_mov_b32_e32 v150, v194
	v_mov_b32_e32 v151, v195
	v_mov_b32_e32 v153, v196
	v_mov_b32_e32 v147, v197
	v_mov_b32_e32 v146, v198
	v_mov_b32_e32 v145, v199
	v_mov_b32_e32 v144, v200
	v_mov_b32_e32 v139, v201
	v_fmamk_f32 v150, v150, 0x3a000000, v246
	v_rsq_f32_e32 v152, v150
	v_pk_mul_f32 v[120:121], v[124:125], v[120:121]
	v_pk_mul_f32 v[122:123], v[126:127], v[122:123]
	v_pk_mul_f32 v[118:119], v[114:115], v[118:119]
	v_mul_f32_e32 v150, 0xbfb8aa3b, v152
	v_pk_mul_f32 v[154:155], v[124:125], v[150:151] op_sel_hi:[1,0]
	v_mul_f32_e32 v152, v152, v152
	v_exp_f32_e32 v154, v154
	v_exp_f32_e32 v155, v155
	v_pk_mul_f32 v[114:115], v[114:115], v[150:151] op_sel_hi:[1,0]
	v_ashrrev_i32_e32 v149, 31, v148
	v_exp_f32_e32 v114, v114
	v_pk_add_f32 v[154:155], v[154:155], 1.0 op_sel_hi:[1,0]
	v_exp_f32_e32 v115, v115
	v_rcp_f32_e32 v154, v154
	v_rcp_f32_e32 v155, v155
	v_pk_mul_f32 v[104:105], v[108:109], v[104:105]
	v_pk_add_f32 v[114:115], v[114:115], 1.0 op_sel_hi:[1,0]
	v_pk_mul_f32 v[106:107], v[110:111], v[106:107]
	v_pk_mul_f32 v[124:125], v[152:153], v[154:155] op_sel_hi:[0,1]
	v_pk_mul_f32 v[120:121], v[120:121], v[124:125]
	v_pk_mul_f32 v[124:125], v[126:127], v[150:151] op_sel_hi:[1,0]
	v_rcp_f32_e32 v114, v114
	v_exp_f32_e32 v124, v124
	v_exp_f32_e32 v125, v125
	v_rcp_f32_e32 v115, v115
	v_pk_mul_f32 v[102:103], v[98:99], v[102:103]
	v_pk_mul_f32 v[88:89], v[92:93], v[88:89]
	v_pk_add_f32 v[124:125], v[124:125], 1.0 op_sel_hi:[1,0]
	v_pk_mul_f32 v[114:115], v[152:153], v[114:115] op_sel_hi:[0,1]
	v_rcp_f32_e32 v124, v124
	v_rcp_f32_e32 v125, v125
	v_pk_mul_f32 v[114:115], v[118:119], v[114:115]
	v_pk_mul_f32 v[90:91], v[94:95], v[90:91]
	v_pk_mul_f32 v[86:87], v[82:83], v[86:87]
	v_pk_mul_f32 v[124:125], v[152:153], v[124:125] op_sel_hi:[0,1]
	v_pk_mul_f32 v[122:123], v[122:123], v[124:125]
	v_pk_mul_f32 v[124:125], v[112:113], v[150:151] op_sel_hi:[1,0]
	v_pk_mul_f32 v[112:113], v[112:113], v[116:117]
	v_exp_f32_e32 v124, v124
	v_exp_f32_e32 v125, v125
	v_pk_mul_f32 v[72:73], v[76:77], v[72:73]
	v_pk_mul_f32 v[74:75], v[78:79], v[74:75]
	v_pk_mul_f32 v[70:71], v[66:67], v[70:71]
	v_pk_add_f32 v[124:125], v[124:125], 1.0 op_sel_hi:[1,0]
	v_pk_mul_f32 v[56:57], v[60:61], v[56:57]
	v_rcp_f32_e32 v124, v124
	v_rcp_f32_e32 v125, v125
	v_pk_mul_f32 v[58:59], v[62:63], v[58:59]
	v_pk_mul_f32 v[54:55], v[50:51], v[54:55]
	v_pk_mul_f32 v[40:41], v[44:45], v[40:41]
	v_pk_mul_f32 v[116:117], v[152:153], v[124:125] op_sel_hi:[0,1]
	v_pk_mul_f32 v[112:113], v[112:113], v[116:117]
	v_cvt_pk_bf16_f32 v116, v120, v121
	v_cvt_pk_bf16_f32 v117, v122, v123
	v_pk_mul_f32 v[42:43], v[46:47], v[42:43]
	v_cvt_pk_bf16_f32 v118, v112, v113
	v_mov_b64_e32 v[112:113], s[24:25]
	v_cvt_pk_bf16_f32 v119, v114, v115
	v_mad_i64_i32 v[120:121], s[2:3], v138, s64, v[112:113]
	v_lshlrev_b64 v[114:115], 1, v[148:149]
	v_lshl_add_u64 v[120:121], v[120:121], 0, v[114:115]
	global_store_dwordx4 v[120:121], v[116:119], off
	v_pk_mul_f32 v[38:39], v[34:35], v[38:39]
	v_pk_mul_f32 v[24:25], v[28:29], v[24:25]
	v_fmamk_f32 v116, v151, 0x3a000000, v246
	v_rsq_f32_e32 v117, v116
	v_pk_mul_f32 v[26:27], v[30:31], v[26:27]
	v_pk_mul_f32 v[22:23], v[18:19], v[22:23]
	v_pk_mul_f32 v[8:9], v[12:13], v[8:9]
	v_mul_f32_e32 v116, 0xbfb8aa3b, v117
	v_pk_mul_f32 v[120:121], v[108:109], v[116:117] op_sel_hi:[1,0]
	v_mul_f32_e32 v118, v117, v117
	v_exp_f32_e32 v120, v120
	v_exp_f32_e32 v121, v121
	v_pk_mul_f32 v[10:11], v[14:15], v[10:11]
	v_pk_mul_f32 v[0:1], v[4:5], v[0:1]
	v_pk_mul_f32 v[2:3], v[6:7], v[2:3]
	v_pk_add_f32 v[120:121], v[120:121], 1.0 op_sel_hi:[1,0]
	s_andn2_b64 vcc, exec, s[38:39]
	v_rcp_f32_e32 v120, v120
	v_rcp_f32_e32 v121, v121
	s_nop 0
	v_pk_mul_f32 v[108:109], v[118:119], v[120:121] op_sel_hi:[0,1]
	v_pk_mul_f32 v[104:105], v[104:105], v[108:109]
	v_pk_mul_f32 v[108:109], v[110:111], v[116:117] op_sel_hi:[1,0]
	s_nop 0
	v_exp_f32_e32 v108, v108
	v_exp_f32_e32 v109, v109
	s_nop 0
	v_pk_add_f32 v[108:109], v[108:109], 1.0 op_sel_hi:[1,0]
	s_nop 0
	v_rcp_f32_e32 v108, v108
	v_rcp_f32_e32 v109, v109
	s_nop 0
	v_pk_mul_f32 v[108:109], v[118:119], v[108:109] op_sel_hi:[0,1]
	v_pk_mul_f32 v[106:107], v[106:107], v[108:109]
	v_pk_mul_f32 v[108:109], v[96:97], v[116:117] op_sel_hi:[1,0]
	v_pk_mul_f32 v[96:97], v[96:97], v[100:101]
	v_exp_f32_e32 v108, v108
	v_exp_f32_e32 v109, v109
	s_nop 0
	v_pk_add_f32 v[108:109], v[108:109], 1.0 op_sel_hi:[1,0]
	s_nop 0
	v_rcp_f32_e32 v108, v108
	v_rcp_f32_e32 v109, v109
	s_nop 0
	v_pk_mul_f32 v[100:101], v[118:119], v[108:109] op_sel_hi:[0,1]
	v_pk_mul_f32 v[100:101], v[96:97], v[100:101]
	v_pk_mul_f32 v[96:97], v[98:99], v[116:117] op_sel_hi:[1,0]
	v_or_b32_e32 v108, 16, v138
	v_exp_f32_e32 v96, v96
	v_exp_f32_e32 v97, v97
	s_nop 0
	v_pk_add_f32 v[96:97], v[96:97], 1.0 op_sel_hi:[1,0]
	s_nop 0
	v_rcp_f32_e32 v96, v96
	v_rcp_f32_e32 v97, v97
	s_nop 0
	v_pk_mul_f32 v[96:97], v[118:119], v[96:97] op_sel_hi:[0,1]
	v_pk_mul_f32 v[102:103], v[102:103], v[96:97]
	v_cvt_pk_bf16_f32 v96, v104, v105
	v_cvt_pk_bf16_f32 v97, v106, v107
	v_cvt_pk_bf16_f32 v98, v100, v101
	v_mad_i64_i32 v[100:101], s[2:3], v108, s64, v[112:113]
	v_lshl_add_u64 v[100:101], v[100:101], 0, v[114:115]
	v_cvt_pk_bf16_f32 v99, v102, v103
	global_store_dwordx4 v[100:101], v[96:99], off
	s_nop 1
	v_fmamk_f32 v96, v153, 0x3a000000, v246
	v_rsq_f32_e32 v97, v96
	s_nop 0
	v_mul_f32_e32 v96, 0xbfb8aa3b, v97
	v_pk_mul_f32 v[100:101], v[92:93], v[96:97] op_sel_hi:[1,0]
	v_mul_f32_e32 v98, v97, v97
	v_exp_f32_e32 v100, v100
	v_exp_f32_e32 v101, v101
	s_nop 0
; __device__ __forceinline__ unsigned cvt_pk_bf16(float lo, float hi) { unsigned r; asm volatile("v_cvt_pk_bf16_f32 %0, %1, %2" : "=v"(r) : "v"(lo), "v"(hi)); return r; }
; __device__ __forceinline__ float rstd_of(float ss, float inv_n) { return __builtin_amdgcn_rsqf(ss * inv_n + RMS_EPS); }
;     __device__ __forceinline__ void operator()(const f32x4 (&acc)[2][2][4][2], const Unit& u, int wr, int wc, int fr, int fq) const {
;     ...
;         for (int ai = 0; ai < 2; ++ai)
; #pragma unroll
;             for (int m = 0; m < 4; ++m) {
;                 const int row = row0 + ai * HALF + m * 16;
;                 const float rs = rstd_of(rsv[ai][m], 1.0f / 2048.0f);
;                 float v[8];
;                 const float cneg = rs * -1.44269504089f, rs2 = rs * rs;
; #pragma unroll
;                 for (int n = 0; n < 2; ++n)
; #pragma unroll
;                     for (int hh = 0; hh < 2; ++hh) {
;                         const f32x2 g = (f32x2){acc[ai][0][m][n][2 * hh], acc[ai][0][m][n][2 * hh + 1]}, up = (f32x2){acc[ai][1][m][n][2 * hh], acc[ai][1][m][n][2 * hh + 1]};
;                         const f32x2 t = g * cneg;
;                         f32x2 d; d.x = __builtin_amdgcn_exp2f(t.x); d.y = __builtin_amdgcn_exp2f(t.y); d = d + 1.0f;
;                         f32x2 r; r.x = __builtin_amdgcn_rcpf(d.x); r.y = __builtin_amdgcn_rcpf(d.y);
;                         const f32x2 o = (g * up) * (r * rs2);
;                         v[n * 4 + 2 * hh] = o.x; v[n * 4 + 2 * hh + 1] = o.y;
;                     }
;                 u32x4 w; w.x = cvt_pk_bf16(v[0], v[1]); w.y = cvt_pk_bf16(v[2], v[3]); w.z = cvt_pk_bf16(v[4], v[5]); w.w = cvt_pk_bf16(v[6], v[7]);
;                 gst<u32x4>(O + (size_t)row * ldo + col0, w);
	v_pk_add_f32 v[100:101], v[100:101], 1.0 op_sel_hi:[1,0]
	s_nop 0
	v_rcp_f32_e32 v100, v100
	v_rcp_f32_e32 v101, v101
	s_nop 0
	v_pk_mul_f32 v[92:93], v[98:99], v[100:101] op_sel_hi:[0,1]
	v_pk_mul_f32 v[88:89], v[88:89], v[92:93]
	v_pk_mul_f32 v[92:93], v[94:95], v[96:97] op_sel_hi:[1,0]
	s_nop 0
	v_exp_f32_e32 v92, v92
	v_exp_f32_e32 v93, v93
	s_nop 0
	v_pk_add_f32 v[92:93], v[92:93], 1.0 op_sel_hi:[1,0]
	s_nop 0
	v_rcp_f32_e32 v92, v92
	v_rcp_f32_e32 v93, v93
	s_nop 0
	v_pk_mul_f32 v[92:93], v[98:99], v[92:93] op_sel_hi:[0,1]
	v_pk_mul_f32 v[90:91], v[90:91], v[92:93]
	v_pk_mul_f32 v[92:93], v[80:81], v[96:97] op_sel_hi:[1,0]
	v_pk_mul_f32 v[80:81], v[80:81], v[84:85]
	v_exp_f32_e32 v92, v92
	v_exp_f32_e32 v93, v93
	s_nop 0
	v_pk_add_f32 v[92:93], v[92:93], 1.0 op_sel_hi:[1,0]
	s_nop 0
	v_rcp_f32_e32 v92, v92
	v_rcp_f32_e32 v93, v93
	s_nop 0
	v_pk_mul_f32 v[84:85], v[98:99], v[92:93] op_sel_hi:[0,1]
	v_pk_mul_f32 v[84:85], v[80:81], v[84:85]
	v_pk_mul_f32 v[80:81], v[82:83], v[96:97] op_sel_hi:[1,0]
	v_or_b32_e32 v92, 32, v138
	v_exp_f32_e32 v80, v80
	v_exp_f32_e32 v81, v81
	s_nop 0
	v_pk_add_f32 v[80:81], v[80:81], 1.0 op_sel_hi:[1,0]
	s_nop 0
	v_rcp_f32_e32 v80, v80
	v_rcp_f32_e32 v81, v81
	s_nop 0
	v_pk_mul_f32 v[80:81], v[98:99], v[80:81] op_sel_hi:[0,1]
	v_pk_mul_f32 v[86:87], v[86:87], v[80:81]
	v_cvt_pk_bf16_f32 v80, v88, v89
	v_cvt_pk_bf16_f32 v81, v90, v91
	v_cvt_pk_bf16_f32 v82, v84, v85
	v_mad_i64_i32 v[84:85], s[2:3], v92, s64, v[112:113]
	v_lshl_add_u64 v[84:85], v[84:85], 0, v[114:115]
	v_cvt_pk_bf16_f32 v83, v86, v87
	global_store_dwordx4 v[84:85], v[80:83], off
	s_nop 1
	v_fmamk_f32 v80, v147, 0x3a000000, v246
	v_rsq_f32_e32 v81, v80
	s_nop 0
	v_mul_f32_e32 v80, 0xbfb8aa3b, v81
	v_pk_mul_f32 v[84:85], v[76:77], v[80:81] op_sel_hi:[1,0]
	v_mul_f32_e32 v82, v81, v81
	v_exp_f32_e32 v84, v84
	v_exp_f32_e32 v85, v85
	s_nop 0
	v_pk_add_f32 v[84:85], v[84:85], 1.0 op_sel_hi:[1,0]
	s_nop 0
	v_rcp_f32_e32 v84, v84
	v_rcp_f32_e32 v85, v85
	s_nop 0
	v_pk_mul_f32 v[76:77], v[82:83], v[84:85] op_sel_hi:[0,1]
	v_pk_mul_f32 v[72:73], v[72:73], v[76:77]
	v_pk_mul_f32 v[76:77], v[78:79], v[80:81] op_sel_hi:[1,0]
	s_nop 0
	v_exp_f32_e32 v76, v76
	v_exp_f32_e32 v77, v77
	s_nop 0
	v_pk_add_f32 v[76:77], v[76:77], 1.0 op_sel_hi:[1,0]
	s_nop 0
	v_rcp_f32_e32 v76, v76
	v_rcp_f32_e32 v77, v77
	s_nop 0
	v_pk_mul_f32 v[76:77], v[82:83], v[76:77] op_sel_hi:[0,1]
	v_pk_mul_f32 v[74:75], v[74:75], v[76:77]
	v_pk_mul_f32 v[76:77], v[64:65], v[80:81] op_sel_hi:[1,0]
	v_pk_mul_f32 v[64:65], v[64:65], v[68:69]
	v_exp_f32_e32 v76, v76
	v_exp_f32_e32 v77, v77
	s_nop 0
	v_pk_add_f32 v[76:77], v[76:77], 1.0 op_sel_hi:[1,0]
	s_nop 0
	v_rcp_f32_e32 v76, v76
	v_rcp_f32_e32 v77, v77
	s_nop 0
	v_pk_mul_f32 v[68:69], v[82:83], v[76:77] op_sel_hi:[0,1]
	v_pk_mul_f32 v[68:69], v[64:65], v[68:69]
	v_pk_mul_f32 v[64:65], v[66:67], v[80:81] op_sel_hi:[1,0]
	v_or_b32_e32 v76, 48, v138
	v_exp_f32_e32 v64, v64
	v_exp_f32_e32 v65, v65
	s_nop 0
	v_pk_add_f32 v[64:65], v[64:65], 1.0 op_sel_hi:[1,0]
	s_nop 0
	v_rcp_f32_e32 v64, v64
	v_rcp_f32_e32 v65, v65
	s_nop 0
	v_pk_mul_f32 v[64:65], v[82:83], v[64:65] op_sel_hi:[0,1]
	v_pk_mul_f32 v[70:71], v[70:71], v[64:65]
	v_cvt_pk_bf16_f32 v64, v72, v73
	v_cvt_pk_bf16_f32 v65, v74, v75
	v_cvt_pk_bf16_f32 v66, v68, v69
	v_mad_i64_i32 v[68:69], s[2:3], v76, s64, v[112:113]
	v_lshl_add_u64 v[68:69], v[68:69], 0, v[114:115]
	v_cvt_pk_bf16_f32 v67, v70, v71
	global_store_dwordx4 v[68:69], v[64:67], off
	s_nop 1
	v_fmamk_f32 v64, v146, 0x3a000000, v246
	v_rsq_f32_e32 v66, v64
	v_add_u32_e32 v65, 0x80, v138
	v_mul_f32_e32 v64, 0xbfb8aa3b, v66
	v_pk_mul_f32 v[68:69], v[60:61], v[64:65] op_sel_hi:[1,0]
	v_mul_f32_e32 v66, v66, v66
	v_exp_f32_e32 v68, v68
	v_exp_f32_e32 v69, v69
	s_nop 0
	v_pk_add_f32 v[68:69], v[68:69], 1.0 op_sel_hi:[1,0]
	s_nop 0
	v_rcp_f32_e32 v68, v68
	v_rcp_f32_e32 v69, v69
	s_nop 0
	v_pk_mul_f32 v[60:61], v[66:67], v[68:69] op_sel_hi:[0,1]
	v_pk_mul_f32 v[56:57], v[56:57], v[60:61]
	v_pk_mul_f32 v[60:61], v[62:63], v[64:65] op_sel_hi:[1,0]
	s_nop 0
	v_exp_f32_e32 v60, v60
	v_exp_f32_e32 v61, v61
	s_nop 0
	v_pk_add_f32 v[60:61], v[60:61], 1.0 op_sel_hi:[1,0]
	s_nop 0
	v_rcp_f32_e32 v60, v60
	v_rcp_f32_e32 v61, v61
	s_nop 0
	v_pk_mul_f32 v[60:61], v[66:67], v[60:61] op_sel_hi:[0,1]
	v_pk_mul_f32 v[58:59], v[58:59], v[60:61]
	v_pk_mul_f32 v[60:61], v[48:49], v[64:65] op_sel_hi:[1,0]
	v_pk_mul_f32 v[48:49], v[48:49], v[52:53]
	v_exp_f32_e32 v60, v60
	v_exp_f32_e32 v61, v61
	s_nop 0
	v_pk_add_f32 v[60:61], v[60:61], 1.0 op_sel_hi:[1,0]
	s_nop 0
	v_rcp_f32_e32 v60, v60
	v_rcp_f32_e32 v61, v61
	s_nop 0
	v_pk_mul_f32 v[52:53], v[66:67], v[60:61] op_sel_hi:[0,1]
	v_pk_mul_f32 v[52:53], v[48:49], v[52:53]
	v_pk_mul_f32 v[48:49], v[50:51], v[64:65] op_sel_hi:[1,0]
	s_nop 0
	v_exp_f32_e32 v48, v48
	v_exp_f32_e32 v49, v49
	s_nop 0
	v_pk_add_f32 v[48:49], v[48:49], 1.0 op_sel_hi:[1,0]
	s_nop 0
	v_rcp_f32_e32 v48, v48
	v_rcp_f32_e32 v49, v49
	s_nop 0
	v_pk_mul_f32 v[48:49], v[66:67], v[48:49] op_sel_hi:[0,1]
	v_pk_mul_f32 v[54:55], v[54:55], v[48:49]
	v_cvt_pk_bf16_f32 v48, v56, v57
	v_cvt_pk_bf16_f32 v49, v58, v59
	v_cvt_pk_bf16_f32 v50, v52, v53
	v_mad_i64_i32 v[52:53], s[2:3], v65, s64, v[112:113]
	v_lshl_add_u64 v[52:53], v[52:53], 0, v[114:115]
	v_cvt_pk_bf16_f32 v51, v54, v55
	global_store_dwordx4 v[52:53], v[48:51], off
	s_nop 1
	v_fmamk_f32 v48, v145, 0x3a000000, v246
	v_rsq_f32_e32 v49, v48
	s_nop 0
	v_mul_f32_e32 v48, 0xbfb8aa3b, v49
	v_pk_mul_f32 v[52:53], v[44:45], v[48:49] op_sel_hi:[1,0]
; __device__ __forceinline__ unsigned cvt_pk_bf16(float lo, float hi) { unsigned r; asm volatile("v_cvt_pk_bf16_f32 %0, %1, %2" : "=v"(r) : "v"(lo), "v"(hi)); return r; }
; __device__ __forceinline__ float rstd_of(float ss, float inv_n) { return __builtin_amdgcn_rsqf(ss * inv_n + RMS_EPS); }
;     __device__ __forceinline__ void operator()(const f32x4 (&acc)[2][2][4][2], const Unit& u, int wr, int wc, int fr, int fq) const {
;     ...
;         for (int ai = 0; ai < 2; ++ai)
; #pragma unroll
;             for (int m = 0; m < 4; ++m) {
;                 const int row = row0 + ai * HALF + m * 16;
;                 const float rs = rstd_of(rsv[ai][m], 1.0f / 2048.0f);
;                 float v[8];
;                 const float cneg = rs * -1.44269504089f, rs2 = rs * rs;
; #pragma unroll
;                 for (int n = 0; n < 2; ++n)
; #pragma unroll
;                     for (int hh = 0; hh < 2; ++hh) {
;                         const f32x2 g = (f32x2){acc[ai][0][m][n][2 * hh], acc[ai][0][m][n][2 * hh + 1]}, up = (f32x2){acc[ai][1][m][n][2 * hh], acc[ai][1][m][n][2 * hh + 1]};
;                         const f32x2 t = g * cneg;
;                         f32x2 d; d.x = __builtin_amdgcn_exp2f(t.x); d.y = __builtin_amdgcn_exp2f(t.y); d = d + 1.0f;
;                         f32x2 r; r.x = __builtin_amdgcn_rcpf(d.x); r.y = __builtin_amdgcn_rcpf(d.y);
;                         const f32x2 o = (g * up) * (r * rs2);
;                         v[n * 4 + 2 * hh] = o.x; v[n * 4 + 2 * hh + 1] = o.y;
;                     }
;                 u32x4 w; w.x = cvt_pk_bf16(v[0], v[1]); w.y = cvt_pk_bf16(v[2], v[3]); w.z = cvt_pk_bf16(v[4], v[5]); w.w = cvt_pk_bf16(v[6], v[7]);
;                 gst<u32x4>(O + (size_t)row * ldo + col0, w);
	v_mul_f32_e32 v50, v49, v49
	v_exp_f32_e32 v52, v52
	v_exp_f32_e32 v53, v53
	s_nop 0
	v_pk_add_f32 v[52:53], v[52:53], 1.0 op_sel_hi:[1,0]
	s_nop 0
	v_rcp_f32_e32 v52, v52
	v_rcp_f32_e32 v53, v53
	s_nop 0
	v_pk_mul_f32 v[44:45], v[50:51], v[52:53] op_sel_hi:[0,1]
	v_pk_mul_f32 v[40:41], v[40:41], v[44:45]
	v_pk_mul_f32 v[44:45], v[46:47], v[48:49] op_sel_hi:[1,0]
	s_nop 0
	v_exp_f32_e32 v44, v44
	v_exp_f32_e32 v45, v45
	s_nop 0
	v_pk_add_f32 v[44:45], v[44:45], 1.0 op_sel_hi:[1,0]
	s_nop 0
	v_rcp_f32_e32 v44, v44
	v_rcp_f32_e32 v45, v45
	s_nop 0
	v_pk_mul_f32 v[44:45], v[50:51], v[44:45] op_sel_hi:[0,1]
	v_pk_mul_f32 v[42:43], v[42:43], v[44:45]
	v_pk_mul_f32 v[44:45], v[32:33], v[48:49] op_sel_hi:[1,0]
	v_pk_mul_f32 v[32:33], v[32:33], v[36:37]
	v_exp_f32_e32 v44, v44
	v_exp_f32_e32 v45, v45
	s_nop 0
	v_pk_add_f32 v[44:45], v[44:45], 1.0 op_sel_hi:[1,0]
	s_nop 0
	v_rcp_f32_e32 v44, v44
	v_rcp_f32_e32 v45, v45
	s_nop 0
	v_pk_mul_f32 v[36:37], v[50:51], v[44:45] op_sel_hi:[0,1]
	v_pk_mul_f32 v[36:37], v[32:33], v[36:37]
	v_pk_mul_f32 v[32:33], v[34:35], v[48:49] op_sel_hi:[1,0]
	v_add_u32_e32 v44, 0x90, v138
	v_exp_f32_e32 v32, v32
	v_exp_f32_e32 v33, v33
	s_nop 0
	v_pk_add_f32 v[32:33], v[32:33], 1.0 op_sel_hi:[1,0]
	s_nop 0
	v_rcp_f32_e32 v32, v32
	v_rcp_f32_e32 v33, v33
	s_nop 0
	v_pk_mul_f32 v[32:33], v[50:51], v[32:33] op_sel_hi:[0,1]
	v_pk_mul_f32 v[38:39], v[38:39], v[32:33]
	v_cvt_pk_bf16_f32 v32, v40, v41
	v_cvt_pk_bf16_f32 v33, v42, v43
	v_cvt_pk_bf16_f32 v34, v36, v37
	v_mad_i64_i32 v[36:37], s[2:3], v44, s64, v[112:113]
	v_lshl_add_u64 v[36:37], v[36:37], 0, v[114:115]
	v_cvt_pk_bf16_f32 v35, v38, v39
	global_store_dwordx4 v[36:37], v[32:35], off
	s_nop 1
	v_fmamk_f32 v32, v144, 0x3a000000, v246
	v_rsq_f32_e32 v33, v32
	s_nop 0
	v_mul_f32_e32 v32, 0xbfb8aa3b, v33
	v_pk_mul_f32 v[36:37], v[28:29], v[32:33] op_sel_hi:[1,0]
	v_mul_f32_e32 v34, v33, v33
	v_exp_f32_e32 v36, v36
	v_exp_f32_e32 v37, v37
	s_nop 0
	v_pk_add_f32 v[36:37], v[36:37], 1.0 op_sel_hi:[1,0]
	s_nop 0
	v_rcp_f32_e32 v36, v36
	v_rcp_f32_e32 v37, v37
	s_nop 0
	v_pk_mul_f32 v[28:29], v[34:35], v[36:37] op_sel_hi:[0,1]
	v_pk_mul_f32 v[24:25], v[24:25], v[28:29]
	v_pk_mul_f32 v[28:29], v[30:31], v[32:33] op_sel_hi:[1,0]
	s_nop 0
	v_exp_f32_e32 v28, v28
	v_exp_f32_e32 v29, v29
	s_nop 0
	v_pk_add_f32 v[28:29], v[28:29], 1.0 op_sel_hi:[1,0]
	s_nop 0
	v_rcp_f32_e32 v28, v28
	v_rcp_f32_e32 v29, v29
	s_nop 0
	v_pk_mul_f32 v[28:29], v[34:35], v[28:29] op_sel_hi:[0,1]
	v_pk_mul_f32 v[26:27], v[26:27], v[28:29]
	v_pk_mul_f32 v[28:29], v[16:17], v[32:33] op_sel_hi:[1,0]
	v_pk_mul_f32 v[16:17], v[16:17], v[20:21]
	v_exp_f32_e32 v28, v28
	v_exp_f32_e32 v29, v29
	s_nop 0
	v_pk_add_f32 v[28:29], v[28:29], 1.0 op_sel_hi:[1,0]
	s_nop 0
	v_rcp_f32_e32 v28, v28
	v_rcp_f32_e32 v29, v29
	s_nop 0
	v_pk_mul_f32 v[20:21], v[34:35], v[28:29] op_sel_hi:[0,1]
	v_pk_mul_f32 v[20:21], v[16:17], v[20:21]
	v_pk_mul_f32 v[16:17], v[18:19], v[32:33] op_sel_hi:[1,0]
	v_add_u32_e32 v28, 0xa0, v138
	v_exp_f32_e32 v16, v16
	v_exp_f32_e32 v17, v17
	s_nop 0
	v_pk_add_f32 v[16:17], v[16:17], 1.0 op_sel_hi:[1,0]
	s_nop 0
	v_rcp_f32_e32 v16, v16
	v_rcp_f32_e32 v17, v17
	s_nop 0
	v_pk_mul_f32 v[16:17], v[34:35], v[16:17] op_sel_hi:[0,1]
	v_pk_mul_f32 v[22:23], v[22:23], v[16:17]
	v_cvt_pk_bf16_f32 v16, v24, v25
	v_cvt_pk_bf16_f32 v17, v26, v27
	v_cvt_pk_bf16_f32 v18, v20, v21
	v_mad_i64_i32 v[20:21], s[2:3], v28, s64, v[112:113]
	v_lshl_add_u64 v[20:21], v[20:21], 0, v[114:115]
	v_cvt_pk_bf16_f32 v19, v22, v23
	global_store_dwordx4 v[20:21], v[16:19], off
	s_nop 1
	v_fmamk_f32 v16, v139, 0x3a000000, v246
	v_rsq_f32_e32 v17, v16
	s_nop 0
	v_mul_f32_e32 v16, 0xbfb8aa3b, v17
	v_pk_mul_f32 v[20:21], v[12:13], v[16:17] op_sel_hi:[1,0]
	v_mul_f32_e32 v18, v17, v17
	v_exp_f32_e32 v20, v20
	v_exp_f32_e32 v21, v21
	s_nop 0
	v_pk_add_f32 v[20:21], v[20:21], 1.0 op_sel_hi:[1,0]
	s_nop 0
	v_rcp_f32_e32 v20, v20
	v_rcp_f32_e32 v21, v21
	s_nop 0
	v_pk_mul_f32 v[12:13], v[18:19], v[20:21] op_sel_hi:[0,1]
	v_pk_mul_f32 v[8:9], v[8:9], v[12:13]
	v_pk_mul_f32 v[12:13], v[14:15], v[16:17] op_sel_hi:[1,0]
	s_nop 0
	v_exp_f32_e32 v12, v12
	v_exp_f32_e32 v13, v13
	s_nop 0
	v_pk_add_f32 v[12:13], v[12:13], 1.0 op_sel_hi:[1,0]
	s_nop 0
	v_rcp_f32_e32 v12, v12
	v_rcp_f32_e32 v13, v13
	s_nop 0
	v_pk_mul_f32 v[12:13], v[18:19], v[12:13] op_sel_hi:[0,1]
	v_pk_mul_f32 v[10:11], v[10:11], v[12:13]
	v_pk_mul_f32 v[12:13], v[4:5], v[16:17] op_sel_hi:[1,0]
	s_nop 0
	v_exp_f32_e32 v12, v12
	v_exp_f32_e32 v13, v13
	s_nop 0
	v_pk_add_f32 v[12:13], v[12:13], 1.0 op_sel_hi:[1,0]
	s_nop 0
	v_rcp_f32_e32 v12, v12
	v_rcp_f32_e32 v13, v13
	s_nop 0
	v_pk_mul_f32 v[4:5], v[18:19], v[12:13] op_sel_hi:[0,1]
	v_pk_mul_f32 v[4:5], v[0:1], v[4:5]
	v_pk_mul_f32 v[0:1], v[6:7], v[16:17] op_sel_hi:[1,0]
	v_add_u32_e32 v12, 0xb0, v138
	v_exp_f32_e32 v0, v0
	v_exp_f32_e32 v1, v1
	s_nop 0
	v_pk_add_f32 v[0:1], v[0:1], 1.0 op_sel_hi:[1,0]
	s_nop 0
	v_rcp_f32_e32 v0, v0
	v_rcp_f32_e32 v1, v1
	s_nop 0
	v_pk_mul_f32 v[0:1], v[18:19], v[0:1] op_sel_hi:[0,1]
	v_pk_mul_f32 v[6:7], v[2:3], v[0:1]
	v_cvt_pk_bf16_f32 v0, v8, v9
	v_cvt_pk_bf16_f32 v1, v10, v11
	v_cvt_pk_bf16_f32 v2, v4, v5
	v_mad_i64_i32 v[4:5], s[2:3], v12, s64, v[112:113]
	v_lshl_add_u64 v[4:5], v[4:5], 0, v[114:115]
	s_mov_b64 s[2:3], -1
	v_cvt_pk_bf16_f32 v3, v6, v7
	global_store_dwordx4 v[4:5], v[0:3], off
	s_cbranch_vccnz .LBB0_22
	s_andn2_b64 vcc, exec, s[22:23]
	s_cbranch_vccnz .LBB0_21
	s_barrier
	s_branch .LBB0_21
